# NSA top-k rank loop: importance compared as unsigned integer keys with the index tie-break folded in (7 -> 4 instructions per token per step)
# speedup vs baseline: 1.0055x; 1.0055x over previous
.LBB0_924:
	s_add_i32 s12, s12, 1
	v_cmp_lt_u32_e32 vcc, s12, v189
	v_readlane_b32 s13, v9, s12
	v_readlane_b32 s20, v10, s12
	v_readlane_b32 s21, v11, s12
	v_readlane_b32 s22, v12, s12
	v_cndmask_b32_e64 v68, 0, 1, vcc
	v_readlane_b32 s23, v13, s12
	v_readlane_b32 s24, v14, s12
	v_readlane_b32 s25, v15, s12
	v_readlane_b32 s26, v48, s12
	v_add_u32_e32 v69, s13, v68
	v_add_u32_e32 v70, s20, v68
	v_add_u32_e32 v71, s21, v68
	v_add_u32_e32 v72, s22, v68
	v_add_u32_e32 v73, s23, v68
	v_add_u32_e32 v74, s24, v68
	v_add_u32_e32 v75, s25, v68
	v_add_u32_e32 v76, s26, v68
	v_cmp_gt_u32_e64 s[32:33], v69, v9
	v_cmp_gt_u32_e64 s[34:35], v70, v10
	v_cmp_gt_u32_e64 s[36:37], v71, v11
	v_cmp_gt_u32_e64 s[38:39], v72, v12
	v_cmp_gt_u32_e64 s[40:41], v73, v13
	v_cmp_gt_u32_e64 s[42:43], v74, v14
	v_cmp_gt_u32_e64 s[44:45], v75, v15
	v_cmp_gt_u32_e64 s[46:47], v76, v48
	v_addc_co_u32_e64 v49, s[32:33], 0, v49, s[32:33]
	v_addc_co_u32_e64 v8, s[34:35], 0, v8, s[34:35]
	v_addc_co_u32_e64 v7, s[36:37], 0, v7, s[36:37]
	v_addc_co_u32_e64 v6, s[38:39], 0, v6, s[38:39]
	v_addc_co_u32_e64 v5, s[40:41], 0, v5, s[40:41]
	v_addc_co_u32_e64 v4, s[42:43], 0, v4, s[42:43]
	v_addc_co_u32_e64 v1, s[44:45], 0, v1, s[44:45]
	v_addc_co_u32_e64 v0, s[46:47], 0, v0, s[46:47]
	s_cmp_lg_u32 s2, s12
	s_cbranch_scc1 .LBB0_924
	v_readlane_b32 s12, v252, 30
	v_cmp_ge_i32_e32 vcc, s0, v189
	v_readlane_b32 s13, v252, 31
	s_sub_i32 s0, 62, s60
	s_and_b64 s[16:17], s[12:13], vcc
	s_lshl_b64 s[12:13], 1, s0
	s_lshl_b64 s[18:19], 1, s61
	v_cmp_gt_u32_e32 vcc, 13, v49
	s_or_b64 s[12:13], s[18:19], s[12:13]
	s_and_b64 s[18:19], s[16:17], vcc
	v_cndmask_b32_e64 v9, 0, 1, s[18:19]
	s_and_b32 s0, s65, 0xffffffc0
	v_cmp_ne_u32_e32 vcc, 0, v9
	s_mov_b64 s[18:19], exec
	v_readlane_b32 s20, v252, 32
	v_readlane_b32 s21, v252, 33
	s_and_b64 s[20:21], s[18:19], s[20:21]
	s_mov_b64 exec, s[20:21]
	s_cbranch_execz .LBB0_927
	s_or_b64 s[20:21], s[12:13], vcc
	s_or_b32 s2, s20, 1
	v_mov_b32_e32 v10, s2
	s_add_i32 s2, s0, 0
	v_mov_b32_e32 v11, s21
	v_mov_b32_e32 v9, s2
	ds_write_b64 v9, v[10:11] offset:43008
